# chained activation-major order; P7 loop-final cluster keeps the baseline barrier placement (its last MFMA reads SrcC v4 which the mid-K seam code overwrites right after the loop)
# speedup vs baseline: 1.0080x; 1.0018x over previous
; #define PG8_STAGE(bufoff, gbase, voff) do { _Pragma("unroll") for (int _i = 0; _i < 2; ++_i) \
;         asm volatile("s_mov_b32 m0, %2\n\ts_nop 0\n\tglobal_load_lds_dwordx4 %0, %1" :: "v"((voff)[_i]), "s"((const char*)(gbase)), "s"(ldsbase + (unsigned)(bufoff) + ldsw + (unsigned)_i * 8192u) : "memory", "m0"); } while (0)
; #define PG8_LDA(dst, b, h) do { _Pragma("unroll") for (int m = 0; m < 4; ++m) _Pragma("unroll") for (int k = 0; k < 2; ++k) dst[m][k] = *(const PG8_LAS bf16x8*)(lds + PG8_SA(b, h) + aoff + m * 2048 + k * 1024); } while (0)
; #define PG8_LDB(dst, b, h) do { _Pragma("unroll") for (int n = 0; n < 2; ++n) _Pragma("unroll") for (int k = 0; k < 2; ++k) dst[n][k] = *(const PG8_LAS bf16x8*)(lds + PG8_SB(b, h) + boff + n * 2048 + k * 1024); } while (0)
; #define PG8_MMA(ai, bj, At, Bt) do { __builtin_amdgcn_s_setprio(1); _Pragma("unroll") for (int m = 0; m < 4; ++m) _Pragma("unroll") for (int n = 0; n < 2; ++n) _Pragma("unroll") for (int k = 0; k < 2; ++k) \
;         acc[ai][bj][m][n] = __builtin_amdgcn_mfma_f32_16x16x32_bf16(Bt[n][k], At[m][k], acc[ai][bj][m][n], 0, 0, 0); __builtin_amdgcn_s_setprio(0); } while (0)
; template <class Epi, class Sched, bool ALIGN_EPI = false, bool SP2 = false>
; __device__ __forceinline__ void gemm_phase(PG8_LAS unsigned char* lds, const Gemm g, const Sched& S, const Epi& E) {
;     ...
;             PG8_LDB(B0, 0, 0); PG8_LDB(B1, 0, 1); PG8_SCHED; PG8_LDA(At, 0, 0); PG8_STAGE(PG8_SA(1, 1), a1 + hstep, voffA);
;             PG8_WAIT_V(8); PG8_WAIT_L(0); PG8_BAR; PG8_MMA(0, 0, At, B0); PG8_MMA(0, 1, At, B1); PG8_BAR; PG8_SCHED;
;             PG8_LDA(At, 0, 1); PG8_STAGE(PG8_SB(0, 0), b2, voffB); PG8_STAGE(PG8_SB(0, 1), b2 + hstep, voffB); PG8_STAGE(PG8_SA(0, 0), a2, voffA);
;             PG8_WAIT_V(8); PG8_WAIT_L(0); PG8_BAR; PG8_MMA(1, 0, At, B0); PG8_MMA(1, 1, At, B1); PG8_BAR; PG8_SCHED;
;             PG8_LDB(B0, 1, 0); PG8_LDB(B1, 1, 1); PG8_SCHED; PG8_LDA(At, 1, 0); PG8_STAGE(PG8_SA(0, 1), a2 + hstep, voffA);
;             PG8_WAIT_V(8); PG8_WAIT_L(0); PG8_BAR; PG8_MMA(0, 0, At, B0); PG8_MMA(0, 1, At, B1); PG8_BAR; PG8_SCHED;
;             PG8_LDA(At, 1, 1); PG8_STAGE(PG8_SB(1, 0), b3, voffB); PG8_STAGE(PG8_SB(1, 1), b3 + hstep, voffB); PG8_STAGE(PG8_SA(1, 0), a3, voffA);
;             PG8_WAIT_V(8); PG8_WAIT_L(0); PG8_BAR; PG8_MMA(1, 0, At, B0); PG8_MMA(1, 1, At, B1); PG8_BAR; PG8_SCHED;
.LBB0_620:
	v_add_u32_e32 v3, 0x10000, v199
	ds_read_b128 v[134:137], v3
	ds_read_b128 v[138:141], v3 offset:1024
	ds_read_b128 v[142:145], v3 offset:2048
	ds_read_b128 v[146:149], v3 offset:3072
	v_add_u32_e32 v3, 0x14000, v199
	s_add_u32 s44, s42, 0x100
	ds_read_b128 v[158:161], v3
	ds_read_b128 v[162:165], v3 offset:1024
	ds_read_b128 v[166:169], v3 offset:2048
	ds_read_b128 v[170:173], v3 offset:3072
	s_addc_u32 s45, s43, 0
	s_cmp_eq_u32 s92, 60
	s_cselect_b32 s56, s88, s44
	s_cselect_b32 s57, s23, s45
	s_cselect_b32 s47, s19, s91
	s_cselect_b32 s46, s89, s90
	s_add_u32 s50, s56, 0x80
	s_addc_u32 s51, s57, 0
	s_add_u32 s54, s46, 0x80
	s_addc_u32 s55, s47, 0
	ds_read_b128 v[174:177], v200
	ds_read_b128 v[178:181], v200 offset:1024
	ds_read_b128 v[182:185], v200 offset:2048
	ds_read_b128 v[186:189], v200 offset:3072
	ds_read_b128 v[190:193], v200 offset:4096
	ds_read_b128 v[202:205], v200 offset:5120
	ds_read_b128 v[206:209], v200 offset:6144
	ds_read_b128 v[210:213], v200 offset:7168
	s_add_u32 s42, s42, 0x100080
	s_addc_u32 s43, s43, 0
	s_mov_b32 m0, s85
	s_nop 0
	global_load_lds_dwordx4 v1, s[42:43]
	s_nop 0
	s_mov_b32 m0, s86
	s_nop 0
	global_load_lds_dwordx4 v195, s[42:43]
	s_waitcnt vmcnt(8)
	s_waitcnt lgkmcnt(0)
	s_barrier
	s_setprio 1
	s_waitcnt lgkmcnt(7)
	v_mfma_f32_16x16x32_bf16 v[130:133], v[134:137], v[174:177], v[130:133]
	v_mfma_f32_16x16x32_bf16 v[126:129], v[142:145], v[174:177], v[126:129]
	s_waitcnt lgkmcnt(5)
	v_mfma_f32_16x16x32_bf16 v[122:125], v[134:137], v[182:185], v[122:125]
	v_mfma_f32_16x16x32_bf16 v[118:121], v[142:145], v[182:185], v[118:121]
	s_waitcnt lgkmcnt(3)
	v_mfma_f32_16x16x32_bf16 v[114:117], v[134:137], v[190:193], v[114:117]
	v_mfma_f32_16x16x32_bf16 v[110:113], v[142:145], v[190:193], v[110:113]
	s_waitcnt lgkmcnt(1)
	v_mfma_f32_16x16x32_bf16 v[106:109], v[134:137], v[206:209], v[106:109]
	v_mfma_f32_16x16x32_bf16 v[102:105], v[142:145], v[206:209], v[102:105]
	v_mfma_f32_16x16x32_bf16 v[130:133], v[138:141], v[178:181], v[130:133]
	v_mfma_f32_16x16x32_bf16 v[126:129], v[146:149], v[178:181], v[126:129]
	v_mfma_f32_16x16x32_bf16 v[122:125], v[138:141], v[186:189], v[122:125]
	v_mfma_f32_16x16x32_bf16 v[118:121], v[146:149], v[186:189], v[118:121]
	v_mfma_f32_16x16x32_bf16 v[114:117], v[138:141], v[202:205], v[114:117]
	v_mfma_f32_16x16x32_bf16 v[110:113], v[146:149], v[202:205], v[110:113]
	s_waitcnt lgkmcnt(0)
	v_mfma_f32_16x16x32_bf16 v[106:109], v[138:141], v[210:213], v[106:109]
	v_mfma_f32_16x16x32_bf16 v[102:105], v[146:149], v[210:213], v[102:105]
	s_setprio 0
	s_setprio 1
	v_mfma_f32_16x16x32_bf16 v[66:69], v[158:161], v[174:177], v[66:69]
	v_mfma_f32_16x16x32_bf16 v[62:65], v[166:169], v[174:177], v[62:65]
	v_mfma_f32_16x16x32_bf16 v[58:61], v[158:161], v[182:185], v[58:61]
	v_mfma_f32_16x16x32_bf16 v[54:57], v[166:169], v[182:185], v[54:57]
	v_mfma_f32_16x16x32_bf16 v[50:53], v[158:161], v[190:193], v[50:53]
	v_mfma_f32_16x16x32_bf16 v[46:49], v[166:169], v[190:193], v[46:49]
	v_mfma_f32_16x16x32_bf16 v[42:45], v[158:161], v[206:209], v[42:45]
	v_mfma_f32_16x16x32_bf16 v[38:41], v[166:169], v[206:209], v[38:41]
	v_mfma_f32_16x16x32_bf16 v[66:69], v[162:165], v[178:181], v[66:69]
	v_mfma_f32_16x16x32_bf16 v[62:65], v[170:173], v[178:181], v[62:65]
	v_mfma_f32_16x16x32_bf16 v[58:61], v[162:165], v[186:189], v[58:61]
	v_mfma_f32_16x16x32_bf16 v[54:57], v[170:173], v[186:189], v[54:57]
	v_mfma_f32_16x16x32_bf16 v[50:53], v[162:165], v[202:205], v[50:53]
	v_mfma_f32_16x16x32_bf16 v[46:49], v[170:173], v[202:205], v[46:49]
	v_mfma_f32_16x16x32_bf16 v[42:45], v[162:165], v[210:213], v[42:45]
	s_setprio 2
	s_barrier
	v_mfma_f32_16x16x32_bf16 v[38:41], v[170:173], v[210:213], v[38:41]
	s_setprio 0
	ds_read_b128 v[174:177], v200 offset:16384
	ds_read_b128 v[178:181], v200 offset:17408
	ds_read_b128 v[182:185], v200 offset:18432
	ds_read_b128 v[186:189], v200 offset:19456
	ds_read_b128 v[190:193], v200 offset:20480
	ds_read_b128 v[202:205], v200 offset:21504
	ds_read_b128 v[206:209], v200 offset:22528
	ds_read_b128 v[252:255], v200 offset:23552
	s_mov_b32 m0, s63
	s_nop 0
	global_load_lds_dwordx4 v194, s[46:47]
	s_add_u32 s42, s46, 0x100000
	s_mov_b32 m0, s64
	s_nop 0
	global_load_lds_dwordx4 v196, s[46:47]
	s_addc_u32 s43, s47, 0
	s_mov_b32 m0, s65
	s_nop 0
	global_load_lds_dwordx4 v194, s[42:43]
	s_nop 0
	s_mov_b32 m0, s66
	s_nop 0
	global_load_lds_dwordx4 v196, s[42:43]
	s_nop 0
	s_mov_b32 m0, s62
	s_nop 0
	global_load_lds_dwordx4 v1, s[56:57]
	s_nop 0
	s_mov_b32 m0, s67
	s_nop 0
	global_load_lds_dwordx4 v195, s[56:57]
	s_waitcnt vmcnt(8)
	s_waitcnt lgkmcnt(0)
	s_barrier
; #define PG8_STAGE(bufoff, gbase, voff) do { _Pragma("unroll") for (int _i = 0; _i < 2; ++_i) \
;         asm volatile("s_mov_b32 m0, %2\n\ts_nop 0\n\tglobal_load_lds_dwordx4 %0, %1" :: "v"((voff)[_i]), "s"((const char*)(gbase)), "s"(ldsbase + (unsigned)(bufoff) + ldsw + (unsigned)_i * 8192u) : "memory", "m0"); } while (0)
; #define PG8_LDA(dst, b, h) do { _Pragma("unroll") for (int m = 0; m < 4; ++m) _Pragma("unroll") for (int k = 0; k < 2; ++k) dst[m][k] = *(const PG8_LAS bf16x8*)(lds + PG8_SA(b, h) + aoff + m * 2048 + k * 1024); } while (0)
; #define PG8_LDB(dst, b, h) do { _Pragma("unroll") for (int n = 0; n < 2; ++n) _Pragma("unroll") for (int k = 0; k < 2; ++k) dst[n][k] = *(const PG8_LAS bf16x8*)(lds + PG8_SB(b, h) + boff + n * 2048 + k * 1024); } while (0)
; #define PG8_MMA(ai, bj, At, Bt) do { __builtin_amdgcn_s_setprio(1); _Pragma("unroll") for (int m = 0; m < 4; ++m) _Pragma("unroll") for (int n = 0; n < 2; ++n) _Pragma("unroll") for (int k = 0; k < 2; ++k) \
;         acc[ai][bj][m][n] = __builtin_amdgcn_mfma_f32_16x16x32_bf16(Bt[n][k], At[m][k], acc[ai][bj][m][n], 0, 0, 0); __builtin_amdgcn_s_setprio(0); } while (0)
; #define PG8_WAIT_V(n) asm volatile("s_waitcnt vmcnt(" #n ")" ::: "memory")
; #define PG8_WAIT_L(n) asm volatile("s_waitcnt lgkmcnt(" #n ")" ::: "memory")
; #define PG8_BAR __builtin_amdgcn_s_barrier()
; #define PG8_SCHED __builtin_amdgcn_sched_barrier(0)
; template <class Epi, class Sched, bool ALIGN_EPI = false, bool SP2 = false>
; __device__ __forceinline__ void gemm_phase(PG8_LAS unsigned char* lds, const Gemm g, const Sched& S, const Epi& E) {
;     ...
;             PG8_WAIT_V(8); PG8_WAIT_L(0); PG8_BAR; PG8_MMA(1, 0, At, B0); PG8_MMA(1, 1, At, B1); PG8_BAR; PG8_SCHED;
;             PG8_LDB(B0, 1, 0); PG8_LDB(B1, 1, 1); PG8_SCHED; PG8_LDA(At, 1, 0); PG8_STAGE(PG8_SA(0, 1), a2 + hstep, voffA);
;             PG8_WAIT_V(8); PG8_WAIT_L(0); PG8_BAR; PG8_MMA(0, 0, At, B0); PG8_MMA(0, 1, At, B1); PG8_BAR; PG8_SCHED;
;             PG8_LDA(At, 1, 1); PG8_STAGE(PG8_SB(1, 0), b3, voffB); PG8_STAGE(PG8_SB(1, 1), b3 + hstep, voffB); PG8_STAGE(PG8_SA(1, 0), a3, voffA);
;             PG8_WAIT_V(8); PG8_WAIT_L(0); PG8_BAR; PG8_MMA(1, 0, At, B0); PG8_MMA(1, 1, At, B1); PG8_BAR; PG8_SCHED;
	s_setprio 1
	s_waitcnt lgkmcnt(7)
	v_mfma_f32_16x16x32_bf16 v[98:101], v[134:137], v[174:177], v[98:101]
	v_mfma_f32_16x16x32_bf16 v[94:97], v[142:145], v[174:177], v[94:97]
	s_waitcnt lgkmcnt(5)
	v_mfma_f32_16x16x32_bf16 v[90:93], v[134:137], v[182:185], v[90:93]
	v_mfma_f32_16x16x32_bf16 v[86:89], v[142:145], v[182:185], v[86:89]
	s_waitcnt lgkmcnt(3)
	v_mfma_f32_16x16x32_bf16 v[82:85], v[134:137], v[190:193], v[82:85]
	v_mfma_f32_16x16x32_bf16 v[78:81], v[142:145], v[190:193], v[78:81]
	s_waitcnt lgkmcnt(1)
	v_mfma_f32_16x16x32_bf16 v[74:77], v[134:137], v[206:209], v[74:77]
	v_mfma_f32_16x16x32_bf16 v[70:73], v[142:145], v[206:209], v[70:73]
	v_mfma_f32_16x16x32_bf16 v[98:101], v[138:141], v[178:181], v[98:101]
	v_mfma_f32_16x16x32_bf16 v[94:97], v[146:149], v[178:181], v[94:97]
	v_mfma_f32_16x16x32_bf16 v[90:93], v[138:141], v[186:189], v[90:93]
	v_mfma_f32_16x16x32_bf16 v[86:89], v[146:149], v[186:189], v[86:89]
	v_mfma_f32_16x16x32_bf16 v[82:85], v[138:141], v[202:205], v[82:85]
	v_mfma_f32_16x16x32_bf16 v[78:81], v[146:149], v[202:205], v[78:81]
	s_waitcnt lgkmcnt(0)
	v_mfma_f32_16x16x32_bf16 v[74:77], v[138:141], v[252:255], v[74:77]
	v_mfma_f32_16x16x32_bf16 v[70:73], v[146:149], v[252:255], v[70:73]
	s_setprio 0
	s_setprio 1
	v_mfma_f32_16x16x32_bf16 v[34:37], v[158:161], v[174:177], v[34:37]
	v_mfma_f32_16x16x32_bf16 v[30:33], v[166:169], v[174:177], v[30:33]
	v_mfma_f32_16x16x32_bf16 v[26:29], v[158:161], v[182:185], v[26:29]
	v_mfma_f32_16x16x32_bf16 v[22:25], v[166:169], v[182:185], v[22:25]
	v_mfma_f32_16x16x32_bf16 v[18:21], v[158:161], v[190:193], v[18:21]
	v_mfma_f32_16x16x32_bf16 v[14:17], v[166:169], v[190:193], v[14:17]
	v_mfma_f32_16x16x32_bf16 v[10:13], v[158:161], v[206:209], v[10:13]
	v_mfma_f32_16x16x32_bf16 v[4:7], v[166:169], v[206:209], v[6:9]
	v_mfma_f32_16x16x32_bf16 v[34:37], v[162:165], v[178:181], v[34:37]
	v_mfma_f32_16x16x32_bf16 v[30:33], v[170:173], v[178:181], v[30:33]
	v_mfma_f32_16x16x32_bf16 v[26:29], v[162:165], v[186:189], v[26:29]
	v_mfma_f32_16x16x32_bf16 v[22:25], v[170:173], v[186:189], v[22:25]
	v_mfma_f32_16x16x32_bf16 v[18:21], v[162:165], v[202:205], v[18:21]
	v_mfma_f32_16x16x32_bf16 v[14:17], v[170:173], v[202:205], v[14:17]
	v_mfma_f32_16x16x32_bf16 v[10:13], v[162:165], v[252:255], v[10:13]
	s_setprio 2
	s_barrier
	v_mfma_f32_16x16x32_bf16 v[4:7], v[170:173], v[252:255], v[4:7]
	s_setprio 0
	v_add_u32_e32 v3, 0x18000, v199
	ds_read_b128 v[134:137], v3
	ds_read_b128 v[138:141], v3 offset:1024
	ds_read_b128 v[142:145], v3 offset:2048
	ds_read_b128 v[146:149], v3 offset:3072
	v_add_u32_e32 v3, 0x1c000, v199
	ds_read_b128 v[158:161], v3
	ds_read_b128 v[162:165], v3 offset:1024
	ds_read_b128 v[166:169], v3 offset:2048
	ds_read_b128 v[248:251], v3 offset:3072
	ds_read_b128 v[174:177], v200 offset:32768
	ds_read_b128 v[178:181], v200 offset:33792
	ds_read_b128 v[182:185], v200 offset:34816
	ds_read_b128 v[186:189], v200 offset:35840
	ds_read_b128 v[190:193], v200 offset:36864
	ds_read_b128 v[202:205], v200 offset:37888
	ds_read_b128 v[206:209], v200 offset:38912
	ds_read_b128 v[210:213], v200 offset:39936
	s_add_u32 s42, s56, 0x100000
	s_addc_u32 s43, s57, 0
	s_mov_b32 m0, s76
	s_nop 0
	global_load_lds_dwordx4 v1, s[42:43]
	s_nop 0
	s_mov_b32 m0, s77
	s_nop 0
	global_load_lds_dwordx4 v195, s[42:43]
	s_waitcnt vmcnt(8)
	s_waitcnt lgkmcnt(0)
	s_barrier
	s_setprio 1
	s_waitcnt lgkmcnt(7)
	v_mfma_f32_16x16x32_bf16 v[130:133], v[134:137], v[174:177], v[130:133]
	v_mfma_f32_16x16x32_bf16 v[126:129], v[142:145], v[174:177], v[126:129]
	s_waitcnt lgkmcnt(5)
	v_mfma_f32_16x16x32_bf16 v[122:125], v[134:137], v[182:185], v[122:125]
	v_mfma_f32_16x16x32_bf16 v[118:121], v[142:145], v[182:185], v[118:121]
	s_waitcnt lgkmcnt(3)
	v_mfma_f32_16x16x32_bf16 v[114:117], v[134:137], v[190:193], v[114:117]
	v_mfma_f32_16x16x32_bf16 v[110:113], v[142:145], v[190:193], v[110:113]
	s_waitcnt lgkmcnt(1)
	v_mfma_f32_16x16x32_bf16 v[106:109], v[134:137], v[206:209], v[106:109]
	v_mfma_f32_16x16x32_bf16 v[102:105], v[142:145], v[206:209], v[102:105]
	v_mfma_f32_16x16x32_bf16 v[130:133], v[138:141], v[178:181], v[130:133]
	v_mfma_f32_16x16x32_bf16 v[126:129], v[146:149], v[178:181], v[126:129]
	v_mfma_f32_16x16x32_bf16 v[122:125], v[138:141], v[186:189], v[122:125]
	v_mfma_f32_16x16x32_bf16 v[118:121], v[146:149], v[186:189], v[118:121]
	v_mfma_f32_16x16x32_bf16 v[114:117], v[138:141], v[202:205], v[114:117]
	v_mfma_f32_16x16x32_bf16 v[110:113], v[146:149], v[202:205], v[110:113]
	s_waitcnt lgkmcnt(0)
	v_mfma_f32_16x16x32_bf16 v[106:109], v[138:141], v[210:213], v[106:109]
	v_mfma_f32_16x16x32_bf16 v[102:105], v[146:149], v[210:213], v[102:105]
	s_setprio 0
	s_setprio 1
	v_mfma_f32_16x16x32_bf16 v[66:69], v[158:161], v[174:177], v[66:69]
	v_mfma_f32_16x16x32_bf16 v[62:65], v[166:169], v[174:177], v[62:65]
	v_mfma_f32_16x16x32_bf16 v[58:61], v[158:161], v[182:185], v[58:61]
	v_mfma_f32_16x16x32_bf16 v[54:57], v[166:169], v[182:185], v[54:57]
	v_mfma_f32_16x16x32_bf16 v[50:53], v[158:161], v[190:193], v[50:53]
	v_mfma_f32_16x16x32_bf16 v[46:49], v[166:169], v[190:193], v[46:49]
	v_mfma_f32_16x16x32_bf16 v[42:45], v[158:161], v[206:209], v[42:45]
	v_mfma_f32_16x16x32_bf16 v[38:41], v[166:169], v[206:209], v[38:41]
	v_mfma_f32_16x16x32_bf16 v[66:69], v[162:165], v[178:181], v[66:69]
	v_mfma_f32_16x16x32_bf16 v[62:65], v[248:251], v[178:181], v[62:65]
	v_mfma_f32_16x16x32_bf16 v[58:61], v[162:165], v[186:189], v[58:61]
	v_mfma_f32_16x16x32_bf16 v[54:57], v[248:251], v[186:189], v[54:57]
	v_mfma_f32_16x16x32_bf16 v[50:53], v[162:165], v[202:205], v[50:53]
	v_mfma_f32_16x16x32_bf16 v[46:49], v[248:251], v[202:205], v[46:49]
	v_mfma_f32_16x16x32_bf16 v[42:45], v[162:165], v[210:213], v[42:45]
	s_setprio 2
	s_barrier
; #define PG8_STAGE(bufoff, gbase, voff) do { _Pragma("unroll") for (int _i = 0; _i < 2; ++_i) \
;         asm volatile("s_mov_b32 m0, %2\n\ts_nop 0\n\tglobal_load_lds_dwordx4 %0, %1" :: "v"((voff)[_i]), "s"((const char*)(gbase)), "s"(ldsbase + (unsigned)(bufoff) + ldsw + (unsigned)_i * 8192u) : "memory", "m0"); } while (0)
; #define PG8_LDA(dst, b, h) do { _Pragma("unroll") for (int m = 0; m < 4; ++m) _Pragma("unroll") for (int k = 0; k < 2; ++k) dst[m][k] = *(const PG8_LAS bf16x8*)(lds + PG8_SA(b, h) + aoff + m * 2048 + k * 1024); } while (0)
; #define PG8_MMA(ai, bj, At, Bt) do { __builtin_amdgcn_s_setprio(1); _Pragma("unroll") for (int m = 0; m < 4; ++m) _Pragma("unroll") for (int n = 0; n < 2; ++n) _Pragma("unroll") for (int k = 0; k < 2; ++k) \
;         acc[ai][bj][m][n] = __builtin_amdgcn_mfma_f32_16x16x32_bf16(Bt[n][k], At[m][k], acc[ai][bj][m][n], 0, 0, 0); __builtin_amdgcn_s_setprio(0); } while (0)
; #define PG8_WAIT_V(n) asm volatile("s_waitcnt vmcnt(" #n ")" ::: "memory")
; #define PG8_WAIT_L(n) asm volatile("s_waitcnt lgkmcnt(" #n ")" ::: "memory")
; #define PG8_BAR __builtin_amdgcn_s_barrier()
; #define PG8_SCHED __builtin_amdgcn_sched_barrier(0)
; template <class Epi, class Sched, bool ALIGN_EPI = false, bool SP2 = false>
; __device__ __forceinline__ void gemm_phase(PG8_LAS unsigned char* lds, const Gemm g, const Sched& S, const Epi& E) {
;     ...
;             if constexpr (epi_has_mid<Epi>::value) { if (t == Epi::MID_T) E.mid(acc, cur, wr, wc, fr, fq); }
;     ...
;             PG8_LDA(At, 1, 1); PG8_STAGE(PG8_SB(1, 0), b3, voffB); PG8_STAGE(PG8_SB(1, 1), b3 + hstep, voffB); PG8_STAGE(PG8_SA(1, 0), a3, voffA);
;             PG8_WAIT_V(8); PG8_WAIT_L(0); PG8_BAR; PG8_MMA(1, 0, At, B0); PG8_MMA(1, 1, At, B1); PG8_BAR; PG8_SCHED;
	v_mfma_f32_16x16x32_bf16 v[38:41], v[248:251], v[210:213], v[38:41]
	s_setprio 0
	ds_read_b128 v[174:177], v200 offset:49152
	ds_read_b128 v[178:181], v200 offset:50176
	ds_read_b128 v[182:185], v200 offset:51200
	ds_read_b128 v[186:189], v200 offset:52224
	ds_read_b128 v[190:193], v200 offset:53248
	ds_read_b128 v[202:205], v200 offset:54272
	ds_read_b128 v[206:209], v200 offset:55296
	ds_read_b128 v[252:255], v200 offset:56320
	s_mov_b32 m0, s78
	s_nop 0
	global_load_lds_dwordx4 v194, s[54:55]
	s_add_u32 s42, s46, 0x100080
	s_mov_b32 m0, s79
	s_nop 0
	global_load_lds_dwordx4 v196, s[54:55]
	s_addc_u32 s43, s47, 0
	s_mov_b32 m0, s83
	s_nop 0
	global_load_lds_dwordx4 v194, s[42:43]
	s_nop 0
	s_mov_b32 m0, s84
	s_nop 0
	global_load_lds_dwordx4 v196, s[42:43]
	s_nop 0
	s_mov_b32 m0, s80
	s_nop 0
	global_load_lds_dwordx4 v1, s[50:51]
	s_nop 0
	s_mov_b32 m0, s82
	s_nop 0
	global_load_lds_dwordx4 v195, s[50:51]
	s_waitcnt vmcnt(8)
	s_waitcnt lgkmcnt(0)
	s_barrier
	s_setprio 1
	s_waitcnt lgkmcnt(7)
	v_mfma_f32_16x16x32_bf16 v[98:101], v[134:137], v[174:177], v[98:101]
	v_mfma_f32_16x16x32_bf16 v[94:97], v[142:145], v[174:177], v[94:97]
	s_waitcnt lgkmcnt(5)
	v_mfma_f32_16x16x32_bf16 v[90:93], v[134:137], v[182:185], v[90:93]
	v_mfma_f32_16x16x32_bf16 v[86:89], v[142:145], v[182:185], v[86:89]
	s_waitcnt lgkmcnt(3)
	v_mfma_f32_16x16x32_bf16 v[82:85], v[134:137], v[190:193], v[82:85]
	v_mfma_f32_16x16x32_bf16 v[78:81], v[142:145], v[190:193], v[78:81]
	s_waitcnt lgkmcnt(1)
	v_mfma_f32_16x16x32_bf16 v[74:77], v[134:137], v[206:209], v[74:77]
	v_mfma_f32_16x16x32_bf16 v[70:73], v[142:145], v[206:209], v[70:73]
	v_mfma_f32_16x16x32_bf16 v[98:101], v[138:141], v[178:181], v[98:101]
	v_mfma_f32_16x16x32_bf16 v[94:97], v[146:149], v[178:181], v[94:97]
	v_mfma_f32_16x16x32_bf16 v[90:93], v[138:141], v[186:189], v[90:93]
	v_mfma_f32_16x16x32_bf16 v[86:89], v[146:149], v[186:189], v[86:89]
	v_mfma_f32_16x16x32_bf16 v[82:85], v[138:141], v[202:205], v[82:85]
	v_mfma_f32_16x16x32_bf16 v[78:81], v[146:149], v[202:205], v[78:81]
	s_waitcnt lgkmcnt(0)
	v_mfma_f32_16x16x32_bf16 v[74:77], v[138:141], v[252:255], v[74:77]
	v_mfma_f32_16x16x32_bf16 v[70:73], v[146:149], v[252:255], v[70:73]
	s_setprio 0
	s_setprio 1
	v_mfma_f32_16x16x32_bf16 v[34:37], v[158:161], v[174:177], v[34:37]
	v_mfma_f32_16x16x32_bf16 v[30:33], v[166:169], v[174:177], v[30:33]
	v_mfma_f32_16x16x32_bf16 v[26:29], v[158:161], v[182:185], v[26:29]
	v_mfma_f32_16x16x32_bf16 v[22:25], v[166:169], v[182:185], v[22:25]
	v_mfma_f32_16x16x32_bf16 v[18:21], v[158:161], v[190:193], v[18:21]
	v_mfma_f32_16x16x32_bf16 v[14:17], v[166:169], v[190:193], v[14:17]
	v_mfma_f32_16x16x32_bf16 v[8:11], v[158:161], v[206:209], v[10:13]
	v_mfma_f32_16x16x32_bf16 v[4:7], v[166:169], v[206:209], v[4:7]
	v_mfma_f32_16x16x32_bf16 v[34:37], v[162:165], v[178:181], v[34:37]
	v_mfma_f32_16x16x32_bf16 v[30:33], v[248:251], v[178:181], v[30:33]
	v_mfma_f32_16x16x32_bf16 v[26:29], v[162:165], v[186:189], v[26:29]
	v_mfma_f32_16x16x32_bf16 v[22:25], v[248:251], v[186:189], v[22:25]
	v_mfma_f32_16x16x32_bf16 v[18:21], v[162:165], v[202:205], v[18:21]
	v_mfma_f32_16x16x32_bf16 v[14:17], v[248:251], v[202:205], v[14:17]
	v_mfma_f32_16x16x32_bf16 v[10:13], v[162:165], v[252:255], v[8:11]
	v_mfma_f32_16x16x32_bf16 v[6:9], v[248:251], v[252:255], v[4:7]
	s_setprio 0
	s_barrier
	s_add_i32 s92, s92, 2
	s_add_u32 s90, s90, 0x100
	s_addc_u32 s91, s91, 0
	s_cmp_gt_u32 s92, 61
	s_cbranch_scc1 .LBB0_622
	s_mov_b64 s[42:43], s[44:45]
	s_cmp_lg_u32 s92, 30
	s_cbranch_scc0 .LBB0_619
	s_branch .LBB0_620
